# conversion engine v7 with default-policy (non-nt) f32 weight loads
# baseline (speedup 1.0000x reference)
; #define GAS __attribute__((address_space(1)))
; __device__ __forceinline__ void conv_load(const ConvItem& it, int lane, f32x4 (&v)[4]) {
;     const int lk = lane >> 3, ln = (lane & 7) * 4;
; #pragma unroll
;     for (int i = 0; i < 4; ++i) v[i] = __builtin_nontemporal_load((const GAS f32x4*)(it.W + (size_t)(it.k0 + 8 * i + lk) * it.N + it.n0 + ln));
; }
.Leng_done:
	ds_read_b128 v[130:133], v167
	ds_read_b128 v[134:137], v167 offset:1024
	ds_read_b128 v[156:159], v167 offset:2048
	ds_read_b128 v[172:175], v167 offset:3072
	ds_read_b128 v[176:179], v168
	ds_read_b128 v[180:183], v168 offset:1024
	ds_read_b128 v[184:187], v168 offset:2048
	ds_read_b128 v[188:191], v168 offset:3072
	s_add_u32 s8, s6, 0xfff00080
	s_addc_u32 s9, s7, -1
	s_cmp_eq_u32 s45, 60
	s_cselect_b32 s37, s1, s9
	s_cselect_b32 s36, s14, s8
	s_cselect_b32 s9, s25, s44
	s_cselect_b32 s8, s27, s33
	v_lshl_add_u64 v[160:161], s[6:7], 0, v[148:149]
	s_add_i32 m0, s55, 0xc000
	ds_read_b128 v[192:195], v169
	ds_read_b128 v[196:199], v169 offset:1024
	ds_read_b128 v[200:203], v169 offset:2048
	ds_read_b128 v[204:207], v169 offset:3072
	ds_read_b128 v[208:211], v169 offset:4096
	ds_read_b128 v[212:215], v169 offset:5120
	ds_read_b128 v[216:219], v169 offset:6144
	ds_read_b128 v[220:223], v169 offset:7168
	global_load_lds_dwordx4 v[160:161], off
	v_lshl_add_u64 v[160:161], s[6:7], 0, v[150:151]
	s_add_i32 m0, s55, 0xe000
	s_nop 0
	global_load_lds_dwordx4 v[160:161], off
	s_cmp_lt_u32 s97, 4
	s_cbranch_scc1 .Leng_ld_done
	v_lshrrev_b32_e32 v254, 3, v1
	v_and_b32_e32 v255, 7, v1
	s_cmp_eq_u32 s97, 8
	s_cbranch_scc0 .Leng_ldB
	v_mul_u32_u24_e32 v254, 0xac00, v254
	v_lshl_add_u32 v254, v255, 4, v254
	global_load_dwordx4 v[232:235], v254, s[98:99]
	s_add_u32 s98, s98, 0x56000
	s_addc_u32 s99, s99, 0
	global_load_dwordx4 v[236:239], v254, s[98:99]
	s_add_u32 s98, s98, 0x56000
	s_addc_u32 s99, s99, 0
	global_load_dwordx4 v[240:243], v254, s[98:99]
	s_add_u32 s98, s98, 0x56000
	s_addc_u32 s99, s99, 0
	global_load_dwordx4 v[246:249], v254, s[98:99]
	v_readlane_b32 s98, v245, 4
	v_readlane_b32 s99, v245, 5
	v_lshrrev_b32_e32 v255, 3, v1
	v_lshlrev_b32_e32 v255, 2, v255
	s_lshl_b32 s93, s93, 7
	s_nop 1
	s_add_u32 s98, s98, s93
	s_addc_u32 s99, s99, 0
	global_load_dword v250, v255, s[98:99]
	global_load_dword v251, v255, s[98:99] offset:32
	global_load_dword v252, v255, s[98:99] offset:64
	global_load_dword v253, v255, s[98:99] offset:96
	s_branch .Leng_ld_done
.Leng_ldB:
	v_lshlrev_b32_e32 v254, 14, v254
	v_lshl_add_u32 v254, v255, 4, v254
	s_nop 0
	global_load_dwordx4 v[232:235], v254, s[98:99]
	s_add_u32 s98, s98, 0x20000
	s_addc_u32 s99, s99, 0
	global_load_dwordx4 v[236:239], v254, s[98:99]
	s_add_u32 s98, s98, 0x20000
	s_addc_u32 s99, s99, 0
	global_load_dwordx4 v[240:243], v254, s[98:99]
	s_add_u32 s98, s98, 0x20000
	s_addc_u32 s99, s99, 0
	global_load_dwordx4 v[246:249], v254, s[98:99]
